# v24 + retention-output unit: issue K/V loads before waiting on the state loads (hoisted above the wait ladder)
# speedup vs baseline: 1.0071x; 1.0071x over previous
.LBB0_1067:
	v_ldexp_f32 v11, v11, s7
	v_log_f32_e32 v11, v11
	v_cndmask_b32_e32 v12, 0, v22, vcc
	s_andn2_b64 vcc, exec, s[4:5]
	v_add_u32_e32 v18, v240, v253
	v_sub_f32_e32 v237, v11, v12
	v_add_u32_e32 v17, v240, v254
	v_add_u32_e32 v16, v240, v252
	v_add_u32_e32 v15, v240, v242
	v_add_u32_e32 v14, v240, v241
	v_add_u32_e32 v13, v240, v243
	v_add_u32_e32 v12, v240, v251
	v_add_u32_e32 v11, v240, v250
	s_cbranch_vccnz .LBB0_1069
	s_mov_b32 s7, s81
	s_lshl_b64 s[4:5], s[6:7], 17
	s_add_u32 s4, s19, s4
	s_addc_u32 s5, s22, s5
	s_mov_b64 s[16:17], s[4:5]
	v_add_u32_e32 v20, 0x10800, v29
	v_lshl_add_u64 v[30:31], s[16:17], 0, v[230:231]
	s_add_u32 s16, s4, 0x2000
	s_addc_u32 s17, s5, 0
	global_load_dwordx4 v[30:33], v[30:31], off nt
	s_nop 0
	v_lshl_add_u64 v[34:35], s[16:17], 0, v[230:231]
	s_add_u32 s16, s4, 0x4000
	s_addc_u32 s17, s5, 0
	global_load_dwordx4 v[34:37], v[34:35], off nt
	s_nop 0
	v_lshl_add_u64 v[38:39], s[16:17], 0, v[230:231]
	s_add_u32 s16, s4, 0x6000
	s_addc_u32 s17, s5, 0
	global_load_dwordx4 v[38:41], v[38:39], off nt
	s_nop 0
	v_lshl_add_u64 v[42:43], s[16:17], 0, v[230:231]
	s_add_u32 s16, s4, 0x8000
	s_addc_u32 s17, s5, 0
	global_load_dwordx4 v[42:45], v[42:43], off nt
	s_nop 0
	v_lshl_add_u64 v[46:47], s[16:17], 0, v[230:231]
	s_add_u32 s16, s4, 0xa000
	s_addc_u32 s17, s5, 0
	global_load_dwordx4 v[46:49], v[46:47], off nt
	s_nop 0
	v_lshl_add_u64 v[50:51], s[16:17], 0, v[230:231]
	s_add_u32 s16, s4, 0xc000
	s_addc_u32 s17, s5, 0
	global_load_dwordx4 v[50:53], v[50:51], off nt
	s_nop 0
	v_lshl_add_u64 v[54:55], s[16:17], 0, v[230:231]
	s_add_u32 s16, s4, 0xe000
	s_addc_u32 s17, s5, 0
	global_load_dwordx4 v[54:57], v[54:55], off nt
	s_nop 0
	v_lshl_add_u64 v[58:59], s[16:17], 0, v[230:231]
	s_add_u32 s16, s4, 0x10000
	s_addc_u32 s17, s5, 0
	global_load_dwordx4 v[58:61], v[58:59], off nt
	s_nop 0
	v_lshl_add_u64 v[62:63], s[16:17], 0, v[230:231]
	s_add_u32 s16, s4, 0x12000
	s_addc_u32 s17, s5, 0
	global_load_dwordx4 v[62:65], v[62:63], off nt
	s_nop 0
	v_lshl_add_u64 v[66:67], s[16:17], 0, v[230:231]
	s_add_u32 s16, s4, 0x14000
	s_addc_u32 s17, s5, 0
	global_load_dwordx4 v[66:69], v[66:67], off nt
	s_nop 0
	v_lshl_add_u64 v[70:71], s[16:17], 0, v[230:231]
	s_add_u32 s16, s4, 0x16000
	s_addc_u32 s17, s5, 0
	global_load_dwordx4 v[70:73], v[70:71], off nt
	s_nop 0
	v_lshl_add_u64 v[74:75], s[16:17], 0, v[230:231]
	s_add_u32 s16, s4, 0x18000
	s_addc_u32 s17, s5, 0
	global_load_dwordx4 v[74:77], v[74:75], off nt
	s_nop 0
	v_lshl_add_u64 v[78:79], s[16:17], 0, v[230:231]
	s_add_u32 s16, s4, 0x1a000
	s_addc_u32 s17, s5, 0
	global_load_dwordx4 v[78:81], v[78:79], off nt
	s_nop 0
	v_lshl_add_u64 v[82:83], s[16:17], 0, v[230:231]
	s_add_u32 s16, s4, 0x1c000
	s_addc_u32 s17, s5, 0
	s_add_u32 s4, s4, 0x1e000
	global_load_dwordx4 v[82:85], v[82:83], off nt
	s_addc_u32 s5, s5, 0
	v_lshl_add_u64 v[86:87], s[16:17], 0, v[230:231]
	global_load_dwordx4 v[86:89], v[86:87], off nt
	s_nop 0
	v_lshl_add_u64 v[90:91], s[4:5], 0, v[230:231]
	global_load_dwordx4 v[90:93], v[90:91], off nt
	s_mul_hi_u32 s4, s13, 0x2a00
	s_add_u32 s5, s10, s14
	s_addc_u32 s4, s11, s4
	s_lshl_b32 s7, s12, 1
	s_add_u32 s7, s5, s7
	s_addc_u32 s13, s4, 0
	s_add_u32 s4, s7, 0x1200
	s_addc_u32 s5, s13, 0
	v_lshl_add_u64 v[130:131], s[4:5], 0, v[234:235]
	s_add_u32 s4, s7, 0x2b200
	s_addc_u32 s5, s13, 0
	global_load_dwordx4 v[126:129], v[130:131], off nt
	global_load_dwordx4 v[130:133], v[130:131], off offset:2048 nt
	v_lshl_add_u64 v[138:139], s[4:5], 0, v[234:235]
	s_add_u32 s4, s7, 0x55200
	s_addc_u32 s5, s13, 0
	global_load_dwordx4 v[134:137], v[138:139], off nt
	global_load_dwordx4 v[138:141], v[138:139], off offset:2048 nt
	v_lshl_add_u64 v[146:147], s[4:5], 0, v[234:235]
	s_add_u32 s4, s7, 0x7f200
	s_addc_u32 s5, s13, 0
	global_load_dwordx4 v[142:145], v[146:147], off nt
	global_load_dwordx4 v[146:149], v[146:147], off offset:2048 nt
	v_lshl_add_u64 v[154:155], s[4:5], 0, v[234:235]
	s_add_u32 s4, s7, 0xa9200
	s_addc_u32 s5, s13, 0
	global_load_dwordx4 v[150:153], v[154:155], off nt
	global_load_dwordx4 v[154:157], v[154:155], off offset:2048 nt
	v_lshl_add_u64 v[162:163], s[4:5], 0, v[234:235]
	s_add_u32 s4, s7, 0xd3200
	s_addc_u32 s5, s13, 0
	global_load_dwordx4 v[158:161], v[162:163], off nt
	global_load_dwordx4 v[162:165], v[162:163], off offset:2048 nt
	v_lshl_add_u64 v[170:171], s[4:5], 0, v[234:235]
	s_add_u32 s4, s7, 0xfd200
	s_addc_u32 s5, s13, 0
	global_load_dwordx4 v[166:169], v[170:171], off nt
	global_load_dwordx4 v[170:173], v[170:171], off offset:2048 nt
	v_lshl_add_u64 v[178:179], s[4:5], 0, v[234:235]
	s_add_u32 s4, s7, 0x127200
	s_addc_u32 s5, s13, 0
	global_load_dwordx4 v[174:177], v[178:179], off nt
	global_load_dwordx4 v[178:181], v[178:179], off offset:2048 nt
	v_lshl_add_u64 v[186:187], s[4:5], 0, v[234:235]
	global_load_dwordx4 v[182:185], v[186:187], off nt
	global_load_dwordx4 v[186:189], v[186:187], off offset:2048 nt
	s_waitcnt vmcnt(31)
	ds_write_b128 v18, v[30:33]
	s_waitcnt vmcnt(30)
	ds_write_b128 v17, v[34:37]
	s_waitcnt vmcnt(29)
	ds_write_b128 v16, v[38:41]
	s_waitcnt vmcnt(28)
	ds_write_b128 v15, v[42:45]
	s_waitcnt vmcnt(27)
	ds_write_b128 v14, v[46:49]
	s_waitcnt vmcnt(26)
	ds_write_b128 v13, v[50:53]
	s_waitcnt vmcnt(25)
	ds_write_b128 v12, v[54:57]
	s_waitcnt vmcnt(24)
	ds_write_b128 v11, v[58:61]
	s_waitcnt vmcnt(23)
	ds_write_b128 v3, v[62:65]
	s_waitcnt vmcnt(22)
	ds_write_b128 v4, v[66:69]
	s_waitcnt vmcnt(21)
	ds_write_b128 v5, v[70:73]
	s_waitcnt vmcnt(20)
	ds_write_b128 v6, v[74:77]
	s_waitcnt vmcnt(19)
	ds_write_b128 v7, v[78:81]
	s_waitcnt vmcnt(18)
	ds_write_b128 v8, v[82:85]
	s_waitcnt vmcnt(17)
	ds_write_b128 v9, v[86:89]
	s_waitcnt vmcnt(16)
	ds_write_b128 v10, v[90:93]
	s_waitcnt lgkmcnt(0)
	s_barrier
	ds_read_b128 v[30:33], v29
	ds_read_b128 v[34:37], v29 offset:64
	s_waitcnt lgkmcnt(1)
	v_mfma_f32_16x16x32_bf16 v[30:33], v[30:33], v[122:125], 0
	ds_read_b128 v[38:41], v29 offset:8512
	ds_read_b128 v[42:45], v29 offset:16960
	ds_read_b128 v[46:49], v29 offset:25408
	s_waitcnt lgkmcnt(3)
	v_mfma_f32_16x16x32_bf16 v[30:33], v[34:37], v[118:121], v[30:33]
	ds_read_b128 v[34:37], v29 offset:128
	ds_read_b128 v[50:53], v29 offset:33856
	ds_read_b128 v[54:57], v29 offset:42304
	s_waitcnt lgkmcnt(2)
	v_mfma_f32_16x16x32_bf16 v[30:33], v[34:37], v[114:117], v[30:33]
	ds_read_b128 v[34:37], v29 offset:192
	ds_read_b128 v[58:61], v29 offset:50752
	ds_read_b128 v[62:65], v29 offset:59200
	s_waitcnt lgkmcnt(2)
	v_mfma_f32_16x16x32_bf16 v[30:33], v[34:37], v[110:113], v[30:33]
	ds_read_b128 v[34:37], v29 offset:256
	s_waitcnt lgkmcnt(0)
	v_mfma_f32_16x16x32_bf16 v[30:33], v[34:37], v[106:109], v[30:33]
	ds_read_b128 v[34:37], v29 offset:320
	s_waitcnt lgkmcnt(0)
	v_mfma_f32_16x16x32_bf16 v[30:33], v[34:37], v[102:105], v[30:33]
	ds_read_b128 v[34:37], v29 offset:384
	s_waitcnt lgkmcnt(0)
	v_mfma_f32_16x16x32_bf16 v[30:33], v[34:37], v[98:101], v[30:33]
	ds_read_b128 v[34:37], v29 offset:448
	s_waitcnt lgkmcnt(0)
	v_mfma_f32_16x16x32_bf16 v[30:33], v[34:37], v[94:97], v[30:33]
	ds_read_b128 v[34:37], v29 offset:8448
	s_waitcnt lgkmcnt(0)
	v_mfma_f32_16x16x32_bf16 v[34:37], v[34:37], v[122:125], 0
	v_mfma_f32_16x16x32_bf16 v[34:37], v[38:41], v[118:121], v[34:37]
	ds_read_b128 v[38:41], v29 offset:8576
	s_waitcnt lgkmcnt(0)
	v_mfma_f32_16x16x32_bf16 v[34:37], v[38:41], v[114:117], v[34:37]
	ds_read_b128 v[38:41], v29 offset:8640
	s_waitcnt lgkmcnt(0)
	v_mfma_f32_16x16x32_bf16 v[34:37], v[38:41], v[110:113], v[34:37]
	ds_read_b128 v[38:41], v29 offset:8704
	s_waitcnt lgkmcnt(0)
	v_mfma_f32_16x16x32_bf16 v[34:37], v[38:41], v[106:109], v[34:37]
	ds_read_b128 v[38:41], v29 offset:8768
	s_waitcnt lgkmcnt(0)
	v_mfma_f32_16x16x32_bf16 v[34:37], v[38:41], v[102:105], v[34:37]
	ds_read_b128 v[38:41], v29 offset:8832
	s_waitcnt lgkmcnt(0)
	v_mfma_f32_16x16x32_bf16 v[34:37], v[38:41], v[98:101], v[34:37]
	ds_read_b128 v[38:41], v29 offset:8896
	s_waitcnt lgkmcnt(0)
	v_mfma_f32_16x16x32_bf16 v[34:37], v[38:41], v[94:97], v[34:37]
	ds_read_b128 v[38:41], v29 offset:16896
	s_waitcnt lgkmcnt(0)
	v_mfma_f32_16x16x32_bf16 v[38:41], v[38:41], v[122:125], 0
	v_mfma_f32_16x16x32_bf16 v[38:41], v[42:45], v[118:121], v[38:41]
	ds_read_b128 v[42:45], v29 offset:17024
	s_waitcnt lgkmcnt(0)
	v_mfma_f32_16x16x32_bf16 v[38:41], v[42:45], v[114:117], v[38:41]
	ds_read_b128 v[42:45], v29 offset:17088
	s_waitcnt lgkmcnt(0)
	v_mfma_f32_16x16x32_bf16 v[38:41], v[42:45], v[110:113], v[38:41]
	ds_read_b128 v[42:45], v29 offset:17152
	s_waitcnt lgkmcnt(0)
	v_mfma_f32_16x16x32_bf16 v[38:41], v[42:45], v[106:109], v[38:41]
	ds_read_b128 v[42:45], v29 offset:17216
	s_waitcnt lgkmcnt(0)
	v_mfma_f32_16x16x32_bf16 v[38:41], v[42:45], v[102:105], v[38:41]
	ds_read_b128 v[42:45], v29 offset:17280
	s_waitcnt lgkmcnt(0)
	v_mfma_f32_16x16x32_bf16 v[38:41], v[42:45], v[98:101], v[38:41]
	ds_read_b128 v[42:45], v29 offset:17344
	s_waitcnt lgkmcnt(0)
	v_mfma_f32_16x16x32_bf16 v[38:41], v[42:45], v[94:97], v[38:41]
	ds_read_b128 v[42:45], v29 offset:25344
	s_waitcnt lgkmcnt(0)
	v_mfma_f32_16x16x32_bf16 v[42:45], v[42:45], v[122:125], 0
	v_mfma_f32_16x16x32_bf16 v[42:45], v[46:49], v[118:121], v[42:45]
	ds_read_b128 v[46:49], v29 offset:25472
	s_waitcnt lgkmcnt(0)
	v_mfma_f32_16x16x32_bf16 v[42:45], v[46:49], v[114:117], v[42:45]
	ds_read_b128 v[46:49], v29 offset:25536
	s_waitcnt lgkmcnt(0)
	v_mfma_f32_16x16x32_bf16 v[42:45], v[46:49], v[110:113], v[42:45]
	ds_read_b128 v[46:49], v29 offset:25600
	s_waitcnt lgkmcnt(0)
	v_mfma_f32_16x16x32_bf16 v[42:45], v[46:49], v[106:109], v[42:45]
	ds_read_b128 v[46:49], v29 offset:25664
	s_waitcnt lgkmcnt(0)
	v_mfma_f32_16x16x32_bf16 v[42:45], v[46:49], v[102:105], v[42:45]
	ds_read_b128 v[46:49], v29 offset:25728
	s_waitcnt lgkmcnt(0)
	v_mfma_f32_16x16x32_bf16 v[42:45], v[46:49], v[98:101], v[42:45]
	ds_read_b128 v[46:49], v29 offset:25792
	s_waitcnt lgkmcnt(0)
	v_mfma_f32_16x16x32_bf16 v[42:45], v[46:49], v[94:97], v[42:45]
	ds_read_b128 v[46:49], v29 offset:33792
	s_waitcnt lgkmcnt(0)
	v_mfma_f32_16x16x32_bf16 v[46:49], v[46:49], v[122:125], 0
	v_mfma_f32_16x16x32_bf16 v[46:49], v[50:53], v[118:121], v[46:49]
	ds_read_b128 v[50:53], v29 offset:33920
	s_waitcnt lgkmcnt(0)
	v_mfma_f32_16x16x32_bf16 v[46:49], v[50:53], v[114:117], v[46:49]
	ds_read_b128 v[50:53], v29 offset:33984
	s_waitcnt lgkmcnt(0)
	v_mfma_f32_16x16x32_bf16 v[46:49], v[50:53], v[110:113], v[46:49]
	ds_read_b128 v[50:53], v29 offset:34048
	s_waitcnt lgkmcnt(0)
	v_mfma_f32_16x16x32_bf16 v[46:49], v[50:53], v[106:109], v[46:49]
	ds_read_b128 v[50:53], v29 offset:34112
	s_waitcnt lgkmcnt(0)
	v_mfma_f32_16x16x32_bf16 v[46:49], v[50:53], v[102:105], v[46:49]
	ds_read_b128 v[50:53], v29 offset:34176
	s_waitcnt lgkmcnt(0)
	v_mfma_f32_16x16x32_bf16 v[46:49], v[50:53], v[98:101], v[46:49]
	ds_read_b128 v[50:53], v29 offset:34240
	s_waitcnt lgkmcnt(0)
	v_mfma_f32_16x16x32_bf16 v[46:49], v[50:53], v[94:97], v[46:49]
	ds_read_b128 v[50:53], v29 offset:42240
	s_waitcnt lgkmcnt(0)
	v_mfma_f32_16x16x32_bf16 v[50:53], v[50:53], v[122:125], 0
	v_mfma_f32_16x16x32_bf16 v[50:53], v[54:57], v[118:121], v[50:53]
	ds_read_b128 v[54:57], v29 offset:42368
	s_waitcnt lgkmcnt(0)
	v_mfma_f32_16x16x32_bf16 v[50:53], v[54:57], v[114:117], v[50:53]
	ds_read_b128 v[54:57], v29 offset:42432
	s_waitcnt lgkmcnt(0)
	v_mfma_f32_16x16x32_bf16 v[50:53], v[54:57], v[110:113], v[50:53]
	ds_read_b128 v[54:57], v29 offset:42496
	s_waitcnt lgkmcnt(0)
	v_mfma_f32_16x16x32_bf16 v[50:53], v[54:57], v[106:109], v[50:53]
	ds_read_b128 v[54:57], v29 offset:42560
	s_waitcnt lgkmcnt(0)
	v_mfma_f32_16x16x32_bf16 v[50:53], v[54:57], v[102:105], v[50:53]
	ds_read_b128 v[54:57], v29 offset:42624
	s_waitcnt lgkmcnt(0)
	v_mfma_f32_16x16x32_bf16 v[50:53], v[54:57], v[98:101], v[50:53]
	ds_read_b128 v[54:57], v29 offset:42688
	s_waitcnt lgkmcnt(0)
	v_mfma_f32_16x16x32_bf16 v[50:53], v[54:57], v[94:97], v[50:53]
	ds_read_b128 v[54:57], v29 offset:50688
	s_waitcnt lgkmcnt(0)
	v_mfma_f32_16x16x32_bf16 v[54:57], v[54:57], v[122:125], 0
	v_mfma_f32_16x16x32_bf16 v[54:57], v[58:61], v[118:121], v[54:57]
	ds_read_b128 v[58:61], v29 offset:50816
	s_waitcnt lgkmcnt(0)
	v_mfma_f32_16x16x32_bf16 v[54:57], v[58:61], v[114:117], v[54:57]
	ds_read_b128 v[58:61], v29 offset:50880
	s_waitcnt lgkmcnt(0)
	v_mfma_f32_16x16x32_bf16 v[54:57], v[58:61], v[110:113], v[54:57]
	ds_read_b128 v[58:61], v29 offset:50944
	s_waitcnt lgkmcnt(0)
	v_mfma_f32_16x16x32_bf16 v[54:57], v[58:61], v[106:109], v[54:57]
	ds_read_b128 v[58:61], v29 offset:51008
	s_waitcnt lgkmcnt(0)
	v_mfma_f32_16x16x32_bf16 v[54:57], v[58:61], v[102:105], v[54:57]
	ds_read_b128 v[58:61], v29 offset:51072
	s_waitcnt lgkmcnt(0)
	v_mfma_f32_16x16x32_bf16 v[54:57], v[58:61], v[98:101], v[54:57]
	ds_read_b128 v[58:61], v29 offset:51136
	s_waitcnt lgkmcnt(0)
	v_mfma_f32_16x16x32_bf16 v[54:57], v[58:61], v[94:97], v[54:57]
	ds_read_b128 v[58:61], v29 offset:59136
	s_waitcnt lgkmcnt(0)
	v_mfma_f32_16x16x32_bf16 v[58:61], v[58:61], v[122:125], 0
	v_mfma_f32_16x16x32_bf16 v[58:61], v[62:65], v[118:121], v[58:61]
	ds_read_b128 v[62:65], v29 offset:59264
	s_waitcnt lgkmcnt(0)
	v_mfma_f32_16x16x32_bf16 v[58:61], v[62:65], v[114:117], v[58:61]
	ds_read_b128 v[62:65], v29 offset:59328
	s_waitcnt lgkmcnt(0)
	v_mfma_f32_16x16x32_bf16 v[58:61], v[62:65], v[110:113], v[58:61]
	ds_read_b128 v[62:65], v29 offset:59392
	s_waitcnt lgkmcnt(0)
	v_mfma_f32_16x16x32_bf16 v[58:61], v[62:65], v[106:109], v[58:61]
	ds_read_b128 v[62:65], v29 offset:59456
	s_waitcnt lgkmcnt(0)
	v_mfma_f32_16x16x32_bf16 v[58:61], v[62:65], v[102:105], v[58:61]
	ds_read_b128 v[62:65], v29 offset:59520
	s_waitcnt lgkmcnt(0)
	v_mfma_f32_16x16x32_bf16 v[58:61], v[62:65], v[98:101], v[58:61]
	ds_read_b128 v[62:65], v29 offset:59584
	s_waitcnt lgkmcnt(0)
	v_mfma_f32_16x16x32_bf16 v[58:61], v[62:65], v[94:97], v[58:61]
	ds_read_b128 v[62:65], v20
	v_add_u32_e32 v20, 0x10840, v29
	ds_read_b128 v[66:69], v20
	s_waitcnt lgkmcnt(1)
	v_mfma_f32_16x16x32_bf16 v[62:65], v[62:65], v[122:125], 0
	v_add_u32_e32 v20, 0x10880, v29
	s_waitcnt lgkmcnt(0)
	v_mfma_f32_16x16x32_bf16 v[62:65], v[66:69], v[118:121], v[62:65]
	ds_read_b128 v[66:69], v20
	v_add_u32_e32 v20, 0x108c0, v29
	s_waitcnt lgkmcnt(0)
	v_mfma_f32_16x16x32_bf16 v[62:65], v[66:69], v[114:117], v[62:65]
	ds_read_b128 v[66:69], v20
	v_add_u32_e32 v20, 0x10900, v29
	s_waitcnt lgkmcnt(0)
	v_mfma_f32_16x16x32_bf16 v[62:65], v[66:69], v[110:113], v[62:65]
	ds_read_b128 v[66:69], v20
	v_add_u32_e32 v20, 0x10940, v29
	s_waitcnt lgkmcnt(0)
	v_mfma_f32_16x16x32_bf16 v[62:65], v[66:69], v[106:109], v[62:65]
	ds_read_b128 v[66:69], v20
	v_add_u32_e32 v20, 0x10980, v29
	s_waitcnt lgkmcnt(0)
	v_mfma_f32_16x16x32_bf16 v[62:65], v[66:69], v[102:105], v[62:65]
	ds_read_b128 v[66:69], v20
	v_add_u32_e32 v20, 0x109c0, v29
	s_waitcnt lgkmcnt(0)
	v_mfma_f32_16x16x32_bf16 v[62:65], v[66:69], v[98:101], v[62:65]
	ds_read_b128 v[66:69], v20
	v_add_u32_e32 v20, 0x12900, v29
	s_waitcnt lgkmcnt(0)
	v_mfma_f32_16x16x32_bf16 v[190:193], v[66:69], v[94:97], v[62:65]
	s_nop 3
	ds_read_b128 v[62:65], v20
	v_add_u32_e32 v20, 0x12940, v29
	ds_read_b128 v[66:69], v20
	s_waitcnt lgkmcnt(1)
	v_mfma_f32_16x16x32_bf16 v[62:65], v[62:65], v[122:125], 0
	v_add_u32_e32 v20, 0x12980, v29
	s_waitcnt lgkmcnt(0)
	v_mfma_f32_16x16x32_bf16 v[62:65], v[66:69], v[118:121], v[62:65]
	ds_read_b128 v[66:69], v20
	v_add_u32_e32 v20, 0x129c0, v29
	s_waitcnt lgkmcnt(0)
	v_mfma_f32_16x16x32_bf16 v[62:65], v[66:69], v[114:117], v[62:65]
	ds_read_b128 v[66:69], v20
	v_add_u32_e32 v20, 0x12a00, v29
	s_waitcnt lgkmcnt(0)
	v_mfma_f32_16x16x32_bf16 v[62:65], v[66:69], v[110:113], v[62:65]
	ds_read_b128 v[66:69], v20
	v_add_u32_e32 v20, 0x12a40, v29
	s_waitcnt lgkmcnt(0)
	v_mfma_f32_16x16x32_bf16 v[62:65], v[66:69], v[106:109], v[62:65]
	ds_read_b128 v[66:69], v20
	v_add_u32_e32 v20, 0x12a80, v29
	s_waitcnt lgkmcnt(0)
	v_mfma_f32_16x16x32_bf16 v[62:65], v[66:69], v[102:105], v[62:65]
	ds_read_b128 v[66:69], v20
	v_add_u32_e32 v20, 0x12ac0, v29
	s_waitcnt lgkmcnt(0)
	v_mfma_f32_16x16x32_bf16 v[62:65], v[66:69], v[98:101], v[62:65]
	ds_read_b128 v[66:69], v20
	v_add_u32_e32 v20, 0x14a00, v29
	s_waitcnt lgkmcnt(0)
	v_mfma_f32_16x16x32_bf16 v[194:197], v[66:69], v[94:97], v[62:65]
	s_nop 3
	ds_read_b128 v[62:65], v20
	v_add_u32_e32 v20, 0x14a40, v29
	ds_read_b128 v[66:69], v20
	s_waitcnt lgkmcnt(1)
	v_mfma_f32_16x16x32_bf16 v[62:65], v[62:65], v[122:125], 0
	v_add_u32_e32 v20, 0x14a80, v29
	s_waitcnt lgkmcnt(0)
	v_mfma_f32_16x16x32_bf16 v[62:65], v[66:69], v[118:121], v[62:65]
	ds_read_b128 v[66:69], v20
	v_add_u32_e32 v20, 0x14ac0, v29
	s_waitcnt lgkmcnt(0)
	v_mfma_f32_16x16x32_bf16 v[62:65], v[66:69], v[114:117], v[62:65]
	ds_read_b128 v[66:69], v20
	v_add_u32_e32 v20, 0x14b00, v29
	s_waitcnt lgkmcnt(0)
	v_mfma_f32_16x16x32_bf16 v[62:65], v[66:69], v[110:113], v[62:65]
	ds_read_b128 v[66:69], v20
	v_add_u32_e32 v20, 0x14b40, v29
	s_waitcnt lgkmcnt(0)
	v_mfma_f32_16x16x32_bf16 v[62:65], v[66:69], v[106:109], v[62:65]
	ds_read_b128 v[66:69], v20
	v_add_u32_e32 v20, 0x14b80, v29
	s_waitcnt lgkmcnt(0)
	v_mfma_f32_16x16x32_bf16 v[62:65], v[66:69], v[102:105], v[62:65]
	ds_read_b128 v[66:69], v20
	v_add_u32_e32 v20, 0x14bc0, v29
	s_waitcnt lgkmcnt(0)
	v_mfma_f32_16x16x32_bf16 v[62:65], v[66:69], v[98:101], v[62:65]
	ds_read_b128 v[66:69], v20
	v_add_u32_e32 v20, 0x16b00, v29
	s_waitcnt lgkmcnt(0)
	v_mfma_f32_16x16x32_bf16 v[198:201], v[66:69], v[94:97], v[62:65]
	s_nop 3
	ds_read_b128 v[62:65], v20
	v_add_u32_e32 v20, 0x16b40, v29
	ds_read_b128 v[66:69], v20
	s_waitcnt lgkmcnt(1)
	v_mfma_f32_16x16x32_bf16 v[62:65], v[62:65], v[122:125], 0
	v_add_u32_e32 v20, 0x16b80, v29
	s_waitcnt lgkmcnt(0)
	v_mfma_f32_16x16x32_bf16 v[62:65], v[66:69], v[118:121], v[62:65]
	ds_read_b128 v[66:69], v20
	v_add_u32_e32 v20, 0x16bc0, v29
	s_waitcnt lgkmcnt(0)
	v_mfma_f32_16x16x32_bf16 v[62:65], v[66:69], v[114:117], v[62:65]
	ds_read_b128 v[66:69], v20
	v_add_u32_e32 v20, 0x16c00, v29
	s_waitcnt lgkmcnt(0)
	v_mfma_f32_16x16x32_bf16 v[62:65], v[66:69], v[110:113], v[62:65]
	ds_read_b128 v[66:69], v20
	v_add_u32_e32 v20, 0x16c40, v29
	s_waitcnt lgkmcnt(0)
	v_mfma_f32_16x16x32_bf16 v[62:65], v[66:69], v[106:109], v[62:65]
	ds_read_b128 v[66:69], v20
	v_add_u32_e32 v20, 0x16c80, v29
	s_waitcnt lgkmcnt(0)
	v_mfma_f32_16x16x32_bf16 v[62:65], v[66:69], v[102:105], v[62:65]
	ds_read_b128 v[66:69], v20
	v_add_u32_e32 v20, 0x16cc0, v29
	s_waitcnt lgkmcnt(0)
	v_mfma_f32_16x16x32_bf16 v[62:65], v[66:69], v[98:101], v[62:65]
	ds_read_b128 v[66:69], v20
	v_add_u32_e32 v20, 0x18c00, v29
	s_waitcnt lgkmcnt(0)
	v_mfma_f32_16x16x32_bf16 v[202:205], v[66:69], v[94:97], v[62:65]
	s_nop 3
	ds_read_b128 v[62:65], v20
	v_add_u32_e32 v20, 0x18c40, v29
	ds_read_b128 v[66:69], v20
	s_waitcnt lgkmcnt(1)
	v_mfma_f32_16x16x32_bf16 v[62:65], v[62:65], v[122:125], 0
	v_add_u32_e32 v20, 0x18c80, v29
	s_waitcnt lgkmcnt(0)
	v_mfma_f32_16x16x32_bf16 v[62:65], v[66:69], v[118:121], v[62:65]
	ds_read_b128 v[66:69], v20
	v_add_u32_e32 v20, 0x18cc0, v29
	s_waitcnt lgkmcnt(0)
	v_mfma_f32_16x16x32_bf16 v[62:65], v[66:69], v[114:117], v[62:65]
	ds_read_b128 v[66:69], v20
	v_add_u32_e32 v20, 0x18d00, v29
	s_waitcnt lgkmcnt(0)
	v_mfma_f32_16x16x32_bf16 v[62:65], v[66:69], v[110:113], v[62:65]
	ds_read_b128 v[66:69], v20
	v_add_u32_e32 v20, 0x18d40, v29
	s_waitcnt lgkmcnt(0)
	v_mfma_f32_16x16x32_bf16 v[62:65], v[66:69], v[106:109], v[62:65]
	ds_read_b128 v[66:69], v20
	v_add_u32_e32 v20, 0x18d80, v29
	s_waitcnt lgkmcnt(0)
	v_mfma_f32_16x16x32_bf16 v[62:65], v[66:69], v[102:105], v[62:65]
	ds_read_b128 v[66:69], v20
	v_add_u32_e32 v20, 0x18dc0, v29
	s_waitcnt lgkmcnt(0)
	v_mfma_f32_16x16x32_bf16 v[62:65], v[66:69], v[98:101], v[62:65]
	ds_read_b128 v[66:69], v20
	v_add_u32_e32 v20, 0x1ad00, v29
	s_waitcnt lgkmcnt(0)
	v_mfma_f32_16x16x32_bf16 v[206:209], v[66:69], v[94:97], v[62:65]
	s_nop 3
	ds_read_b128 v[62:65], v20
	v_add_u32_e32 v20, 0x1ad40, v29
	ds_read_b128 v[66:69], v20
	s_waitcnt lgkmcnt(1)
	v_mfma_f32_16x16x32_bf16 v[62:65], v[62:65], v[122:125], 0
	v_add_u32_e32 v20, 0x1ad80, v29
	s_waitcnt lgkmcnt(0)
	v_mfma_f32_16x16x32_bf16 v[62:65], v[66:69], v[118:121], v[62:65]
	ds_read_b128 v[66:69], v20
	v_add_u32_e32 v20, 0x1adc0, v29
	s_waitcnt lgkmcnt(0)
	v_mfma_f32_16x16x32_bf16 v[62:65], v[66:69], v[114:117], v[62:65]
	ds_read_b128 v[66:69], v20
	v_add_u32_e32 v20, 0x1ae00, v29
	s_waitcnt lgkmcnt(0)
	v_mfma_f32_16x16x32_bf16 v[62:65], v[66:69], v[110:113], v[62:65]
	ds_read_b128 v[66:69], v20
	v_add_u32_e32 v20, 0x1ae40, v29
	s_waitcnt lgkmcnt(0)
	v_mfma_f32_16x16x32_bf16 v[62:65], v[66:69], v[106:109], v[62:65]
	ds_read_b128 v[66:69], v20
	v_add_u32_e32 v20, 0x1ae80, v29
	s_waitcnt lgkmcnt(0)
	v_mfma_f32_16x16x32_bf16 v[62:65], v[66:69], v[102:105], v[62:65]
	ds_read_b128 v[66:69], v20
	v_add_u32_e32 v20, 0x1aec0, v29
	s_waitcnt lgkmcnt(0)
	v_mfma_f32_16x16x32_bf16 v[62:65], v[66:69], v[98:101], v[62:65]
	ds_read_b128 v[66:69], v20
	v_add_u32_e32 v20, 0x1ce00, v29
	s_waitcnt lgkmcnt(0)
	v_mfma_f32_16x16x32_bf16 v[210:213], v[66:69], v[94:97], v[62:65]
	s_nop 3
	ds_read_b128 v[62:65], v20
	v_add_u32_e32 v20, 0x1ce40, v29
	ds_read_b128 v[66:69], v20
	s_waitcnt lgkmcnt(1)
	v_mfma_f32_16x16x32_bf16 v[62:65], v[62:65], v[122:125], 0
	v_add_u32_e32 v20, 0x1ce80, v29
	s_waitcnt lgkmcnt(0)
	v_mfma_f32_16x16x32_bf16 v[62:65], v[66:69], v[118:121], v[62:65]
	ds_read_b128 v[66:69], v20
	v_add_u32_e32 v20, 0x1cec0, v29
	s_waitcnt lgkmcnt(0)
	v_mfma_f32_16x16x32_bf16 v[62:65], v[66:69], v[114:117], v[62:65]
	ds_read_b128 v[66:69], v20
	v_add_u32_e32 v20, 0x1cf00, v29
	s_waitcnt lgkmcnt(0)
	v_mfma_f32_16x16x32_bf16 v[62:65], v[66:69], v[110:113], v[62:65]
	ds_read_b128 v[66:69], v20
	v_add_u32_e32 v20, 0x1cf40, v29
	s_waitcnt lgkmcnt(0)
	v_mfma_f32_16x16x32_bf16 v[62:65], v[66:69], v[106:109], v[62:65]
	ds_read_b128 v[66:69], v20
	v_add_u32_e32 v20, 0x1cf80, v29
	s_waitcnt lgkmcnt(0)
	v_mfma_f32_16x16x32_bf16 v[62:65], v[66:69], v[102:105], v[62:65]
	ds_read_b128 v[66:69], v20
	v_add_u32_e32 v20, 0x1cfc0, v29
	s_waitcnt lgkmcnt(0)
	v_mfma_f32_16x16x32_bf16 v[62:65], v[66:69], v[98:101], v[62:65]
	ds_read_b128 v[66:69], v20
	v_add_u32_e32 v20, 0x1ef00, v29
	s_waitcnt lgkmcnt(0)
	v_mfma_f32_16x16x32_bf16 v[214:217], v[66:69], v[94:97], v[62:65]
	s_nop 3
	ds_read_b128 v[62:65], v20
	v_add_u32_e32 v20, 0x1ef40, v29
	ds_read_b128 v[66:69], v20
	s_waitcnt lgkmcnt(1)
	v_mfma_f32_16x16x32_bf16 v[62:65], v[62:65], v[122:125], 0
	v_add_u32_e32 v20, 0x1ef80, v29
	s_waitcnt lgkmcnt(0)
	v_mfma_f32_16x16x32_bf16 v[62:65], v[66:69], v[118:121], v[62:65]
	ds_read_b128 v[66:69], v20
	v_add_u32_e32 v20, 0x1efc0, v29
	s_waitcnt lgkmcnt(0)
	v_mfma_f32_16x16x32_bf16 v[62:65], v[66:69], v[114:117], v[62:65]
	ds_read_b128 v[66:69], v20
	v_add_u32_e32 v20, 0x1f000, v29
	s_waitcnt lgkmcnt(0)
	v_mfma_f32_16x16x32_bf16 v[62:65], v[66:69], v[110:113], v[62:65]
	ds_read_b128 v[66:69], v20
	v_add_u32_e32 v20, 0x1f040, v29
	s_waitcnt lgkmcnt(0)
	v_mfma_f32_16x16x32_bf16 v[62:65], v[66:69], v[106:109], v[62:65]
	ds_read_b128 v[66:69], v20
	v_add_u32_e32 v20, 0x1f080, v29
	s_waitcnt lgkmcnt(0)
	v_mfma_f32_16x16x32_bf16 v[62:65], v[66:69], v[102:105], v[62:65]
	ds_read_b128 v[66:69], v20
	v_add_u32_e32 v20, 0x1f0c0, v29
	s_waitcnt lgkmcnt(0)
	v_mfma_f32_16x16x32_bf16 v[62:65], v[66:69], v[98:101], v[62:65]
	ds_read_b128 v[66:69], v20
	v_add_u32_e32 v20, 1, v233
	v_cvt_f32_i32_e32 v20, v20
	s_waitcnt lgkmcnt(0)
	v_mfma_f32_16x16x32_bf16 v[218:221], v[66:69], v[94:97], v[62:65]
	v_mul_f32_e32 v20, v237, v20
	v_exp_f32_e32 v20, v20
	s_barrier
	v_pk_mul_f32 v[92:93], v[20:21], v[32:33] op_sel_hi:[0,1]
	v_pk_mul_f32 v[90:91], v[20:21], v[30:31] op_sel_hi:[0,1]
	v_pk_mul_f32 v[88:89], v[20:21], v[36:37] op_sel_hi:[0,1]
	v_pk_mul_f32 v[86:87], v[20:21], v[34:35] op_sel_hi:[0,1]
	v_pk_mul_f32 v[84:85], v[20:21], v[40:41] op_sel_hi:[0,1]
	v_pk_mul_f32 v[82:83], v[20:21], v[38:39] op_sel_hi:[0,1]
	v_pk_mul_f32 v[80:81], v[20:21], v[44:45] op_sel_hi:[0,1]
	v_pk_mul_f32 v[78:79], v[20:21], v[42:43] op_sel_hi:[0,1]
	v_pk_mul_f32 v[76:77], v[20:21], v[48:49] op_sel_hi:[0,1]
	v_pk_mul_f32 v[74:75], v[20:21], v[46:47] op_sel_hi:[0,1]
	v_pk_mul_f32 v[72:73], v[20:21], v[52:53] op_sel_hi:[0,1]
	v_pk_mul_f32 v[70:71], v[20:21], v[50:51] op_sel_hi:[0,1]
	v_pk_mul_f32 v[68:69], v[20:21], v[56:57] op_sel_hi:[0,1]
	v_pk_mul_f32 v[66:67], v[20:21], v[54:55] op_sel_hi:[0,1]
	v_pk_mul_f32 v[64:65], v[20:21], v[60:61] op_sel_hi:[0,1]
	v_pk_mul_f32 v[62:63], v[20:21], v[58:59] op_sel_hi:[0,1]
	v_pk_mul_f32 v[60:61], v[20:21], v[192:193] op_sel_hi:[0,1]
	v_pk_mul_f32 v[58:59], v[20:21], v[190:191] op_sel_hi:[0,1]
	v_pk_mul_f32 v[56:57], v[20:21], v[196:197] op_sel_hi:[0,1]
	v_pk_mul_f32 v[54:55], v[20:21], v[194:195] op_sel_hi:[0,1]
	v_pk_mul_f32 v[52:53], v[20:21], v[200:201] op_sel_hi:[0,1]
	v_pk_mul_f32 v[50:51], v[20:21], v[198:199] op_sel_hi:[0,1]
	v_pk_mul_f32 v[48:49], v[20:21], v[204:205] op_sel_hi:[0,1]
	v_pk_mul_f32 v[46:47], v[20:21], v[202:203] op_sel_hi:[0,1]
	v_pk_mul_f32 v[44:45], v[20:21], v[208:209] op_sel_hi:[0,1]
	v_pk_mul_f32 v[42:43], v[20:21], v[206:207] op_sel_hi:[0,1]
	v_pk_mul_f32 v[40:41], v[20:21], v[212:213] op_sel_hi:[0,1]
	v_pk_mul_f32 v[38:39], v[20:21], v[210:211] op_sel_hi:[0,1]
	v_pk_mul_f32 v[36:37], v[20:21], v[216:217] op_sel_hi:[0,1]
	v_pk_mul_f32 v[34:35], v[20:21], v[214:215] op_sel_hi:[0,1]
	v_pk_mul_f32 v[32:33], v[20:21], v[220:221] op_sel_hi:[0,1]
	v_pk_mul_f32 v[30:31], v[20:21], v[218:219] op_sel_hi:[0,1]
	s_branch .LBB0_1070
